# out-phase epilogue de-serialised: g vector loaded once, 16 x-row loads in flight with counted vmcnt waits (was per-row load-wait-store)
# speedup vs baseline: 1.0742x; 1.0096x over previous
.LBB0_512:
	global_load_dwordx4 v[152:155], v[130:131], off
	v_mov_b32_e32 v192, v136
	s_mov_b64 s[62:63], 0x4000
	v_lshlrev_b64 v[156:157], 11, v[192:193]
	v_lshl_add_u64 v[158:159], v[128:129], 0, v[156:157]
	v_lshl_add_u64 v[160:161], v[132:133], 0, v[156:157]
	global_load_dwordx2 v[164:165], v[158:159], off
	v_lshl_add_u64 v[158:159], v[158:159], 0, s[62:63]
	global_load_dwordx2 v[166:167], v[158:159], off
	v_lshl_add_u64 v[158:159], v[158:159], 0, s[62:63]
	global_load_dwordx2 v[168:169], v[158:159], off
	v_lshl_add_u64 v[158:159], v[158:159], 0, s[62:63]
	global_load_dwordx2 v[170:171], v[158:159], off
	v_lshl_add_u64 v[158:159], v[158:159], 0, s[62:63]
	global_load_dwordx2 v[172:173], v[158:159], off
	v_lshl_add_u64 v[158:159], v[158:159], 0, s[62:63]
	global_load_dwordx2 v[174:175], v[158:159], off
	v_lshl_add_u64 v[158:159], v[158:159], 0, s[62:63]
	global_load_dwordx2 v[176:177], v[158:159], off
	v_lshl_add_u64 v[158:159], v[158:159], 0, s[62:63]
	global_load_dwordx2 v[178:179], v[158:159], off
	v_lshl_add_u64 v[158:159], v[158:159], 0, s[62:63]
	global_load_dwordx2 v[180:181], v[158:159], off
	v_lshl_add_u64 v[158:159], v[158:159], 0, s[62:63]
	global_load_dwordx2 v[182:183], v[158:159], off
	v_lshl_add_u64 v[158:159], v[158:159], 0, s[62:63]
	global_load_dwordx2 v[184:185], v[158:159], off
	v_lshl_add_u64 v[158:159], v[158:159], 0, s[62:63]
	global_load_dwordx2 v[186:187], v[158:159], off
	v_lshl_add_u64 v[158:159], v[158:159], 0, s[62:63]
	global_load_dwordx2 v[196:197], v[158:159], off
	v_lshl_add_u64 v[158:159], v[158:159], 0, s[62:63]
	global_load_dwordx2 v[198:199], v[158:159], off
	v_lshl_add_u64 v[158:159], v[158:159], 0, s[62:63]
	global_load_dwordx2 v[200:201], v[158:159], off
	v_lshl_add_u64 v[158:159], v[158:159], 0, s[62:63]
	global_load_dwordx2 v[202:203], v[158:159], off
	ds_read_b128 v[138:141], v137
	s_waitcnt vmcnt(15)
	v_lshlrev_b32_e32 v150, 16, v164
	v_and_b32_e32 v151, 0xffff0000, v164
	v_lshlrev_b32_e32 v142, 16, v165
	v_and_b32_e32 v143, 0xffff0000, v165
	s_waitcnt lgkmcnt(0)
	v_pk_mul_f32 v[138:139], v[138:139], v[152:153]
	v_pk_mul_f32 v[140:141], v[140:141], v[154:155]
	v_pk_fma_f32 v[138:139], v[150:151], s[56:57], v[138:139] op_sel_hi:[1,0,1]
	v_pk_fma_f32 v[140:141], v[142:143], s[56:57], v[140:141] op_sel_hi:[1,0,1]
	v_cvt_pk_bf16_f32 v144, v138, v139
	v_cvt_pk_bf16_f32 v145, v140, v141
	global_store_dwordx2 v[160:161], v[144:145], off
	v_lshl_add_u64 v[160:161], v[160:161], 0, s[62:63]
	ds_read_b128 v[138:141], v137 offset:4224
	s_waitcnt vmcnt(15)
	v_lshlrev_b32_e32 v150, 16, v166
	v_and_b32_e32 v151, 0xffff0000, v166
	v_lshlrev_b32_e32 v142, 16, v167
	v_and_b32_e32 v143, 0xffff0000, v167
	s_waitcnt lgkmcnt(0)
	v_pk_mul_f32 v[138:139], v[138:139], v[152:153]
	v_pk_mul_f32 v[140:141], v[140:141], v[154:155]
	v_pk_fma_f32 v[138:139], v[150:151], s[56:57], v[138:139] op_sel_hi:[1,0,1]
	v_pk_fma_f32 v[140:141], v[142:143], s[56:57], v[140:141] op_sel_hi:[1,0,1]
	v_cvt_pk_bf16_f32 v146, v138, v139
	v_cvt_pk_bf16_f32 v147, v140, v141
	global_store_dwordx2 v[160:161], v[146:147], off
	v_lshl_add_u64 v[160:161], v[160:161], 0, s[62:63]
	ds_read_b128 v[138:141], v137 offset:8448
	s_waitcnt vmcnt(15)
	v_lshlrev_b32_e32 v150, 16, v168
	v_and_b32_e32 v151, 0xffff0000, v168
	v_lshlrev_b32_e32 v142, 16, v169
	v_and_b32_e32 v143, 0xffff0000, v169
	s_waitcnt lgkmcnt(0)
	v_pk_mul_f32 v[138:139], v[138:139], v[152:153]
	v_pk_mul_f32 v[140:141], v[140:141], v[154:155]
	v_pk_fma_f32 v[138:139], v[150:151], s[56:57], v[138:139] op_sel_hi:[1,0,1]
	v_pk_fma_f32 v[140:141], v[142:143], s[56:57], v[140:141] op_sel_hi:[1,0,1]
	v_cvt_pk_bf16_f32 v144, v138, v139
	v_cvt_pk_bf16_f32 v145, v140, v141
	global_store_dwordx2 v[160:161], v[144:145], off
	v_lshl_add_u64 v[160:161], v[160:161], 0, s[62:63]
	ds_read_b128 v[138:141], v137 offset:12672
	s_waitcnt vmcnt(15)
	v_lshlrev_b32_e32 v150, 16, v170
	v_and_b32_e32 v151, 0xffff0000, v170
	v_lshlrev_b32_e32 v142, 16, v171
	v_and_b32_e32 v143, 0xffff0000, v171
	s_waitcnt lgkmcnt(0)
	v_pk_mul_f32 v[138:139], v[138:139], v[152:153]
	v_pk_mul_f32 v[140:141], v[140:141], v[154:155]
	v_pk_fma_f32 v[138:139], v[150:151], s[56:57], v[138:139] op_sel_hi:[1,0,1]
	v_pk_fma_f32 v[140:141], v[142:143], s[56:57], v[140:141] op_sel_hi:[1,0,1]
	v_cvt_pk_bf16_f32 v146, v138, v139
	v_cvt_pk_bf16_f32 v147, v140, v141
	global_store_dwordx2 v[160:161], v[146:147], off
	v_lshl_add_u64 v[160:161], v[160:161], 0, s[62:63]
	ds_read_b128 v[138:141], v137 offset:16896
	s_waitcnt vmcnt(15)
	v_lshlrev_b32_e32 v150, 16, v172
	v_and_b32_e32 v151, 0xffff0000, v172
	v_lshlrev_b32_e32 v142, 16, v173
	v_and_b32_e32 v143, 0xffff0000, v173
	s_waitcnt lgkmcnt(0)
	v_pk_mul_f32 v[138:139], v[138:139], v[152:153]
	v_pk_mul_f32 v[140:141], v[140:141], v[154:155]
	v_pk_fma_f32 v[138:139], v[150:151], s[56:57], v[138:139] op_sel_hi:[1,0,1]
	v_pk_fma_f32 v[140:141], v[142:143], s[56:57], v[140:141] op_sel_hi:[1,0,1]
	v_cvt_pk_bf16_f32 v144, v138, v139
	v_cvt_pk_bf16_f32 v145, v140, v141
	global_store_dwordx2 v[160:161], v[144:145], off
	v_lshl_add_u64 v[160:161], v[160:161], 0, s[62:63]
	ds_read_b128 v[138:141], v137 offset:21120
	s_waitcnt vmcnt(15)
	v_lshlrev_b32_e32 v150, 16, v174
	v_and_b32_e32 v151, 0xffff0000, v174
	v_lshlrev_b32_e32 v142, 16, v175
	v_and_b32_e32 v143, 0xffff0000, v175
	s_waitcnt lgkmcnt(0)
	v_pk_mul_f32 v[138:139], v[138:139], v[152:153]
	v_pk_mul_f32 v[140:141], v[140:141], v[154:155]
	v_pk_fma_f32 v[138:139], v[150:151], s[56:57], v[138:139] op_sel_hi:[1,0,1]
	v_pk_fma_f32 v[140:141], v[142:143], s[56:57], v[140:141] op_sel_hi:[1,0,1]
	v_cvt_pk_bf16_f32 v146, v138, v139
	v_cvt_pk_bf16_f32 v147, v140, v141
	global_store_dwordx2 v[160:161], v[146:147], off
	v_lshl_add_u64 v[160:161], v[160:161], 0, s[62:63]
	ds_read_b128 v[138:141], v137 offset:25344
	s_waitcnt vmcnt(15)
	v_lshlrev_b32_e32 v150, 16, v176
	v_and_b32_e32 v151, 0xffff0000, v176
	v_lshlrev_b32_e32 v142, 16, v177
	v_and_b32_e32 v143, 0xffff0000, v177
	s_waitcnt lgkmcnt(0)
	v_pk_mul_f32 v[138:139], v[138:139], v[152:153]
	v_pk_mul_f32 v[140:141], v[140:141], v[154:155]
	v_pk_fma_f32 v[138:139], v[150:151], s[56:57], v[138:139] op_sel_hi:[1,0,1]
	v_pk_fma_f32 v[140:141], v[142:143], s[56:57], v[140:141] op_sel_hi:[1,0,1]
	v_cvt_pk_bf16_f32 v144, v138, v139
	v_cvt_pk_bf16_f32 v145, v140, v141
	global_store_dwordx2 v[160:161], v[144:145], off
	v_lshl_add_u64 v[160:161], v[160:161], 0, s[62:63]
	ds_read_b128 v[138:141], v137 offset:29568
	s_waitcnt vmcnt(15)
	v_lshlrev_b32_e32 v150, 16, v178
	v_and_b32_e32 v151, 0xffff0000, v178
	v_lshlrev_b32_e32 v142, 16, v179
	v_and_b32_e32 v143, 0xffff0000, v179
	s_waitcnt lgkmcnt(0)
	v_pk_mul_f32 v[138:139], v[138:139], v[152:153]
	v_pk_mul_f32 v[140:141], v[140:141], v[154:155]
	v_pk_fma_f32 v[138:139], v[150:151], s[56:57], v[138:139] op_sel_hi:[1,0,1]
	v_pk_fma_f32 v[140:141], v[142:143], s[56:57], v[140:141] op_sel_hi:[1,0,1]
	v_cvt_pk_bf16_f32 v146, v138, v139
	v_cvt_pk_bf16_f32 v147, v140, v141
	global_store_dwordx2 v[160:161], v[146:147], off
	v_lshl_add_u64 v[160:161], v[160:161], 0, s[62:63]
	ds_read_b128 v[138:141], v137 offset:33792
	s_waitcnt vmcnt(15)
	v_lshlrev_b32_e32 v150, 16, v180
	v_and_b32_e32 v151, 0xffff0000, v180
	v_lshlrev_b32_e32 v142, 16, v181
	v_and_b32_e32 v143, 0xffff0000, v181
	s_waitcnt lgkmcnt(0)
	v_pk_mul_f32 v[138:139], v[138:139], v[152:153]
	v_pk_mul_f32 v[140:141], v[140:141], v[154:155]
	v_pk_fma_f32 v[138:139], v[150:151], s[56:57], v[138:139] op_sel_hi:[1,0,1]
	v_pk_fma_f32 v[140:141], v[142:143], s[56:57], v[140:141] op_sel_hi:[1,0,1]
	v_cvt_pk_bf16_f32 v144, v138, v139
	v_cvt_pk_bf16_f32 v145, v140, v141
	global_store_dwordx2 v[160:161], v[144:145], off
	v_lshl_add_u64 v[160:161], v[160:161], 0, s[62:63]
	ds_read_b128 v[138:141], v137 offset:38016
	s_waitcnt vmcnt(15)
	v_lshlrev_b32_e32 v150, 16, v182
	v_and_b32_e32 v151, 0xffff0000, v182
	v_lshlrev_b32_e32 v142, 16, v183
	v_and_b32_e32 v143, 0xffff0000, v183
	s_waitcnt lgkmcnt(0)
	v_pk_mul_f32 v[138:139], v[138:139], v[152:153]
	v_pk_mul_f32 v[140:141], v[140:141], v[154:155]
	v_pk_fma_f32 v[138:139], v[150:151], s[56:57], v[138:139] op_sel_hi:[1,0,1]
	v_pk_fma_f32 v[140:141], v[142:143], s[56:57], v[140:141] op_sel_hi:[1,0,1]
	v_cvt_pk_bf16_f32 v146, v138, v139
	v_cvt_pk_bf16_f32 v147, v140, v141
	global_store_dwordx2 v[160:161], v[146:147], off
	v_lshl_add_u64 v[160:161], v[160:161], 0, s[62:63]
	ds_read_b128 v[138:141], v137 offset:42240
	s_waitcnt vmcnt(15)
	v_lshlrev_b32_e32 v150, 16, v184
	v_and_b32_e32 v151, 0xffff0000, v184
	v_lshlrev_b32_e32 v142, 16, v185
	v_and_b32_e32 v143, 0xffff0000, v185
	s_waitcnt lgkmcnt(0)
	v_pk_mul_f32 v[138:139], v[138:139], v[152:153]
	v_pk_mul_f32 v[140:141], v[140:141], v[154:155]
	v_pk_fma_f32 v[138:139], v[150:151], s[56:57], v[138:139] op_sel_hi:[1,0,1]
	v_pk_fma_f32 v[140:141], v[142:143], s[56:57], v[140:141] op_sel_hi:[1,0,1]
	v_cvt_pk_bf16_f32 v144, v138, v139
	v_cvt_pk_bf16_f32 v145, v140, v141
	global_store_dwordx2 v[160:161], v[144:145], off
	v_lshl_add_u64 v[160:161], v[160:161], 0, s[62:63]
	ds_read_b128 v[138:141], v137 offset:46464
	s_waitcnt vmcnt(15)
	v_lshlrev_b32_e32 v150, 16, v186
	v_and_b32_e32 v151, 0xffff0000, v186
	v_lshlrev_b32_e32 v142, 16, v187
	v_and_b32_e32 v143, 0xffff0000, v187
	s_waitcnt lgkmcnt(0)
	v_pk_mul_f32 v[138:139], v[138:139], v[152:153]
	v_pk_mul_f32 v[140:141], v[140:141], v[154:155]
	v_pk_fma_f32 v[138:139], v[150:151], s[56:57], v[138:139] op_sel_hi:[1,0,1]
	v_pk_fma_f32 v[140:141], v[142:143], s[56:57], v[140:141] op_sel_hi:[1,0,1]
	v_cvt_pk_bf16_f32 v146, v138, v139
	v_cvt_pk_bf16_f32 v147, v140, v141
	global_store_dwordx2 v[160:161], v[146:147], off
	v_lshl_add_u64 v[160:161], v[160:161], 0, s[62:63]
	ds_read_b128 v[138:141], v137 offset:50688
	s_waitcnt vmcnt(15)
	v_lshlrev_b32_e32 v150, 16, v196
	v_and_b32_e32 v151, 0xffff0000, v196
	v_lshlrev_b32_e32 v142, 16, v197
	v_and_b32_e32 v143, 0xffff0000, v197
	s_waitcnt lgkmcnt(0)
	v_pk_mul_f32 v[138:139], v[138:139], v[152:153]
	v_pk_mul_f32 v[140:141], v[140:141], v[154:155]
	v_pk_fma_f32 v[138:139], v[150:151], s[56:57], v[138:139] op_sel_hi:[1,0,1]
	v_pk_fma_f32 v[140:141], v[142:143], s[56:57], v[140:141] op_sel_hi:[1,0,1]
	v_cvt_pk_bf16_f32 v144, v138, v139
	v_cvt_pk_bf16_f32 v145, v140, v141
	global_store_dwordx2 v[160:161], v[144:145], off
	v_lshl_add_u64 v[160:161], v[160:161], 0, s[62:63]
	ds_read_b128 v[138:141], v137 offset:54912
	s_waitcnt vmcnt(15)
	v_lshlrev_b32_e32 v150, 16, v198
	v_and_b32_e32 v151, 0xffff0000, v198
	v_lshlrev_b32_e32 v142, 16, v199
	v_and_b32_e32 v143, 0xffff0000, v199
	s_waitcnt lgkmcnt(0)
	v_pk_mul_f32 v[138:139], v[138:139], v[152:153]
	v_pk_mul_f32 v[140:141], v[140:141], v[154:155]
	v_pk_fma_f32 v[138:139], v[150:151], s[56:57], v[138:139] op_sel_hi:[1,0,1]
	v_pk_fma_f32 v[140:141], v[142:143], s[56:57], v[140:141] op_sel_hi:[1,0,1]
	v_cvt_pk_bf16_f32 v146, v138, v139
	v_cvt_pk_bf16_f32 v147, v140, v141
	global_store_dwordx2 v[160:161], v[146:147], off
	v_lshl_add_u64 v[160:161], v[160:161], 0, s[62:63]
	ds_read_b128 v[138:141], v137 offset:59136
	s_waitcnt vmcnt(15)
	v_lshlrev_b32_e32 v150, 16, v200
	v_and_b32_e32 v151, 0xffff0000, v200
	v_lshlrev_b32_e32 v142, 16, v201
	v_and_b32_e32 v143, 0xffff0000, v201
	s_waitcnt lgkmcnt(0)
	v_pk_mul_f32 v[138:139], v[138:139], v[152:153]
	v_pk_mul_f32 v[140:141], v[140:141], v[154:155]
	v_pk_fma_f32 v[138:139], v[150:151], s[56:57], v[138:139] op_sel_hi:[1,0,1]
	v_pk_fma_f32 v[140:141], v[142:143], s[56:57], v[140:141] op_sel_hi:[1,0,1]
	v_cvt_pk_bf16_f32 v144, v138, v139
	v_cvt_pk_bf16_f32 v145, v140, v141
	global_store_dwordx2 v[160:161], v[144:145], off
	v_lshl_add_u64 v[160:161], v[160:161], 0, s[62:63]
	ds_read_b128 v[138:141], v137 offset:63360
	s_waitcnt vmcnt(15)
	v_lshlrev_b32_e32 v150, 16, v202
	v_and_b32_e32 v151, 0xffff0000, v202
	v_lshlrev_b32_e32 v142, 16, v203
	v_and_b32_e32 v143, 0xffff0000, v203
	s_waitcnt lgkmcnt(0)
	v_pk_mul_f32 v[138:139], v[138:139], v[152:153]
	v_pk_mul_f32 v[140:141], v[140:141], v[154:155]
	v_pk_fma_f32 v[138:139], v[150:151], s[56:57], v[138:139] op_sel_hi:[1,0,1]
	v_pk_fma_f32 v[140:141], v[142:143], s[56:57], v[140:141] op_sel_hi:[1,0,1]
	v_cvt_pk_bf16_f32 v146, v138, v139
	v_cvt_pk_bf16_f32 v147, v140, v141
	global_store_dwordx2 v[160:161], v[146:147], off
	s_mov_b32 s4, 1
	s_mov_b64 s[2:3], 0
	s_and_b64 vcc, exec, s[0:1]
	s_barrier
	s_cbranch_vccz .LBB0_509
	v_readlane_b32 s24, v254, 58
	v_readlane_b32 s25, v254, 59
